# w_in conversion tiles prefetch their 4 row-block loads; phase-0 x copy/convert items processed 4 at a time
# speedup vs baseline: 1.7198x; 1.0048x over previous
; DI int in_colmap(int n) {
;   if (n < 1280) return n;
;   if (n < 1920) return n + 32;
;   if (n < 2688) return n + 44;
;   if (n < 2720) return n - 2688 + 1280;
;   if (n < 2732) return n - 2720 + 1952;
;   if (n < 2736) return n;
;   if (n < 2752) return -1;
;   if (n < 6848) return n - 16;
;   return -1;
; }
; template <bool MAP = false>
; DI void conv_tile(const float* __restrict__ src, int N, int K, bfu* __restrict__ dst, const float* __restrict__ g,
;                   int tk, int tn, char* smem, int ldk = -1) {
;     ...
;   for (int j = 0; j < 4; ++j) {
;     int k = (tid >> 4) + 16 * j, n4 = (tid & 15) * 4;
;     int gn = tn * 64 + n4, gk = tk * 64 + k;
;     float4 v = make_float4(0.f, 0.f, 0.f, 0.f);
;     const int og = MAP ? in_colmap(gn) : (gn < N ? gn : -1);
;     if (og >= 0) v = *(const float4*)(src + (size_t)gk * N + og);
.LBB0_68:
	s_andn2_b64 vcc, exec, s[2:3]
	s_cbranch_vccnz .LBB0_26
	s_mul_hi_i32 s2, s6, 0x4bda12f7
	s_lshr_b32 s3, s2, 31
	s_ashr_i32 s2, s2, 5
	s_add_i32 s2, s2, s3
	s_mul_i32 s3, s2, 0x6c
	v_mov_b32_e32 v9, v224
	s_sub_i32 s3, s6, s3
	s_lshl_b32 s7, s3, 6
	v_lshlrev_b32_e32 v0, 2, v9
	v_and_b32_e32 v5, 60, v0
	s_lshl_b32 s34, s2, 6
	v_or_b32_e32 v0, s7, v5
	s_movk_i32 s2, 0x500
	s_cmpk_lt_u32 s7, 0xa80
	v_cmp_gt_i32_e32 vcc, s2, v0
	s_cselect_b64 s[4:5], -1, 0
	s_add_i32 s2, s7, 0xfffff540
	s_cmpk_lt_u32 s2, 0x1000
	v_add_u32_e32 v1, -16, v0
	s_cselect_b64 s[2:3], -1, 0
	v_cndmask_b32_e64 v1, -1, v1, s[2:3]
	s_movk_i32 s2, 0xab0
	v_cmp_gt_u32_e64 s[2:3], s2, v0
	v_add_u32_e32 v2, 0xfffffd00, v0
	v_add_u32_e32 v3, 0xfffffa80, v0
	v_cndmask_b32_e64 v1, v1, v0, s[2:3]
	s_movk_i32 s2, 0xaac
	v_cmp_gt_u32_e64 s[2:3], s2, v0
	v_ashrrev_i32_e32 v4, 4, v9
	v_add_u32_e32 v6, s34, v4
	v_cndmask_b32_e64 v1, v1, v2, s[2:3]
	s_movk_i32 s2, 0xaa0
	v_cmp_gt_u32_e64 s[2:3], s2, v0
	s_barrier
	s_nop 0
	v_cndmask_b32_e64 v1, v1, v3, s[2:3]
	s_or_b64 s[2:3], vcc, s[4:5]
	s_cmpk_lt_u32 s7, 0x780
	s_cselect_b32 s4, 32, 44
	v_mov_b32_e32 v2, s4
	v_cndmask_b32_e64 v2, v2, 0, vcc
	v_add_u32_e32 v0, v2, v0
	v_cndmask_b32_e64 v188, v1, v0, s[2:3]
	v_mov_b32_e32 v0, 0
	v_cmp_lt_i32_e64 s[2:3], -1, v188
	v_mov_b32_e32 v1, v0
	v_mov_b32_e32 v2, v0
	v_mov_b32_e32 v3, v0
	s_and_saveexec_b64 s[4:5], s[2:3]
	s_cbranch_execz .LBB0_71
	v_mov_b64_e32 v[0:1], s[92:93]
	s_movk_i32 s12, 0x6ac0
	v_mad_i64_i32 v[0:1], s[28:29], v6, s12, v[0:1]
	v_lshl_add_u64 v[0:1], v[188:189], 2, v[0:1]
	v_add_u32_e32 v210, 16, v6
	v_mov_b64_e32 v[212:213], s[92:93]
	v_mad_i64_i32 v[212:213], s[98:99], v210, s12, v[212:213]
	v_lshl_add_u64 v[212:213], v[188:189], 2, v[212:213]
	global_load_dwordx4 v[240:243], v[212:213], off
	v_add_u32_e32 v210, 32, v6
	v_mov_b64_e32 v[212:213], s[92:93]
	v_mad_i64_i32 v[212:213], s[98:99], v210, s12, v[212:213]
	v_lshl_add_u64 v[212:213], v[188:189], 2, v[212:213]
	global_load_dwordx4 v[244:247], v[212:213], off
	v_add_u32_e32 v210, 48, v6
	v_mov_b64_e32 v[212:213], s[92:93]
	v_mad_i64_i32 v[212:213], s[98:99], v210, s12, v[212:213]
	v_lshl_add_u64 v[212:213], v[188:189], 2, v[212:213]
	global_load_dwordx4 v[248:251], v[212:213], off
	global_load_dwordx4 v[0:3], v[0:1], off

; DI int TID() { int t = threadIdx.x; asm volatile("" : "+v"(t)); return t; }
; DI unsigned pk2(float a, float b) { f32x2_t v = {a, b}; bf16x2_t r_ = __builtin_convertvector(v, bf16x2_t); return __builtin_bit_cast(unsigned, r_); }
; DI void phase_convert(const Params& p, int L, char* smem) {
;     ...
;   for (int it = blockIdx.x; it < total; it += gridDim.x) {
;     ...
;     else {
;       size_t e = (size_t)(it - CV_NA - CV_NB - CV_NC) * 2048 + TID() * 8;
;       float4 a = *(const float4*)(p.x + e), b = *(const float4*)(p.x + e + 4);
;       *(float4*)(p.out + e) = a; *(float4*)(p.out + e + 4) = b;
;       *(u32x4*)(p.xb2 + e) = (u32x4){pk2(a.x, a.y), pk2(a.z, a.w), pk2(b.x, b.y), pk2(b.z, b.w)};
;     }
.LBB0_1906:
	s_cmpk_gt_i32 s33, 0x6bf
	s_mov_b64 s[2:3], -1
	s_cbranch_scc0 .LBB0_1993
	s_cmpk_gt_u32 s33, 0x783
	s_cbranch_scc0 .LBB0_1952
	s_cmpk_gt_u32 s33, 0x1ac3
	s_cbranch_scc0 .LBB0_1910
	v_readlane_b32 s16, v254, 46
	v_readlane_b32 s17, v254, 47
	v_readlane_b32 s28, v253, 44
	v_readlane_b32 s29, v253, 45
	v_readlane_b32 s2, v254, 38
	v_readlane_b32 s3, v254, 39
	s_nop 3
	s_load_dword s4, s[2:3], 0x0
	v_lshlrev_b32_e32 v8, 5, v224
	s_waitcnt lgkmcnt(0)
.Lx_loop:
	s_add_i32 s5, s33, 0xffffe53c
	s_mov_b32 s7, s33
	s_mov_b32 s6, 0
	s_cmpk_gt_i32 s7, 0x3ac3
	s_cbranch_scc1 .Lx_issued
	s_lshl_b32 s8, s5, 13
	v_add_u32_e32 v40, s8, v8
	global_load_dwordx4 v[0:3], v40, s[16:17]
	global_load_dwordx4 v[4:7], v40, s[16:17] offset:16
	s_add_i32 s6, s6, 1
	s_add_i32 s5, s5, s4
	s_add_i32 s7, s7, s4
	s_cmpk_gt_i32 s7, 0x3ac3
	s_cbranch_scc1 .Lx_issued
	s_lshl_b32 s8, s5, 13
	v_add_u32_e32 v41, s8, v8
	global_load_dwordx4 v[12:15], v41, s[16:17]
	global_load_dwordx4 v[16:19], v41, s[16:17] offset:16
	s_add_i32 s6, s6, 1
	s_add_i32 s5, s5, s4
	s_add_i32 s7, s7, s4
	s_cmpk_gt_i32 s7, 0x3ac3
	s_cbranch_scc1 .Lx_issued
	s_lshl_b32 s8, s5, 13
	v_add_u32_e32 v42, s8, v8
	global_load_dwordx4 v[20:23], v42, s[16:17]
	global_load_dwordx4 v[24:27], v42, s[16:17] offset:16
	s_add_i32 s6, s6, 1
	s_add_i32 s5, s5, s4
	s_add_i32 s7, s7, s4
	s_cmpk_gt_i32 s7, 0x3ac3
	s_cbranch_scc1 .Lx_issued
	s_lshl_b32 s8, s5, 13
	v_add_u32_e32 v43, s8, v8
	global_load_dwordx4 v[28:31], v43, s[16:17]
	global_load_dwordx4 v[32:35], v43, s[16:17] offset:16
	s_add_i32 s6, s6, 1
	s_add_i32 s5, s5, s4
	s_add_i32 s7, s7, s4
.Lx_issued:
	s_waitcnt vmcnt(0)
	s_cmp_lt_u32 s6, 1
	s_cbranch_scc1 .Lx_stored
	global_store_dwordx4 v40, v[0:3], s[28:29]
	global_store_dwordx4 v40, v[4:7], s[28:29] offset:16
	v_cvt_pk_bf16_f32 v36, v0, v1
	v_cvt_pk_bf16_f32 v37, v2, v3
	v_cvt_pk_bf16_f32 v38, v4, v5
	v_cvt_pk_bf16_f32 v39, v6, v7
	v_lshrrev_b32_e32 v44, 1, v40
	global_store_dwordx4 v44, v[36:39], s[38:39]
	s_nop 1
	s_cmp_lt_u32 s6, 2
	s_cbranch_scc1 .Lx_stored
	global_store_dwordx4 v41, v[12:15], s[28:29]
	global_store_dwordx4 v41, v[16:19], s[28:29] offset:16
	v_cvt_pk_bf16_f32 v36, v12, v13
	v_cvt_pk_bf16_f32 v37, v14, v15
	v_cvt_pk_bf16_f32 v38, v16, v17
	v_cvt_pk_bf16_f32 v39, v18, v19
	v_lshrrev_b32_e32 v44, 1, v41
	global_store_dwordx4 v44, v[36:39], s[38:39]
	s_nop 1
	s_cmp_lt_u32 s6, 3
	s_cbranch_scc1 .Lx_stored
	global_store_dwordx4 v42, v[20:23], s[28:29]
	global_store_dwordx4 v42, v[24:27], s[28:29] offset:16
	v_cvt_pk_bf16_f32 v36, v20, v21
	v_cvt_pk_bf16_f32 v37, v22, v23
	v_cvt_pk_bf16_f32 v38, v24, v25
	v_cvt_pk_bf16_f32 v39, v26, v27
	v_lshrrev_b32_e32 v44, 1, v42
	global_store_dwordx4 v44, v[36:39], s[38:39]
	s_nop 1
	s_cmp_lt_u32 s6, 4
	s_cbranch_scc1 .Lx_stored
	global_store_dwordx4 v43, v[28:31], s[28:29]
	global_store_dwordx4 v43, v[32:35], s[28:29] offset:16
	v_cvt_pk_bf16_f32 v36, v28, v29
	v_cvt_pk_bf16_f32 v37, v30, v31
	v_cvt_pk_bf16_f32 v38, v32, v33
	v_cvt_pk_bf16_f32 v39, v34, v35
	v_lshrrev_b32_e32 v44, 1, v43
	global_store_dwordx4 v44, v[36:39], s[38:39]
	s_nop 1
.Lx_stored:
	s_mov_b32 s33, s7
	s_cmpk_gt_i32 s33, 0x3ac3
	s_cbranch_scc0 .Lx_loop
	s_mov_b64 s[2:3], 0

; DI int in_colmap(int n) {
;   if (n < 1280) return n;
;   if (n < 1920) return n + 32;
;   if (n < 2688) return n + 44;
;   if (n < 2720) return n - 2688 + 1280;
;   if (n < 2732) return n - 2720 + 1952;
;   if (n < 2736) return n;
;   if (n < 2752) return -1;
;   if (n < 6848) return n - 16;
;   return -1;
; }
; template <bool MAP = false>
; DI void conv_tile(const float* __restrict__ src, int N, int K, bfu* __restrict__ dst, const float* __restrict__ g,
;                   int tk, int tn, char* smem, int ldk = -1) {
;     ...
;   for (int j = 0; j < 4; ++j) {
;     int k = (tid >> 4) + 16 * j, n4 = (tid & 15) * 4;
;     int gn = tn * 64 + n4, gk = tk * 64 + k;
;     float4 v = make_float4(0.f, 0.f, 0.f, 0.f);
;     const int og = MAP ? in_colmap(gn) : (gn < N ? gn : -1);
;     if (og >= 0) v = *(const float4*)(src + (size_t)gk * N + og);
.LBB0_1993:
	s_andn2_b64 vcc, exec, s[2:3]
	s_cbranch_vccnz .LBB0_1905
	s_mul_hi_i32 s2, s33, 0x4bda12f7
	s_lshr_b32 s3, s2, 31
	s_ashr_i32 s2, s2, 5
	s_add_i32 s2, s2, s3
	s_mul_i32 s3, s2, 0x6c
	v_mov_b32_e32 v9, v224
	s_sub_i32 s3, s33, s3
	s_lshl_b32 s12, s3, 6
	v_lshlrev_b32_e32 v0, 2, v9
	v_and_b32_e32 v5, 60, v0
	s_lshl_b32 s20, s2, 6
	v_or_b32_e32 v0, s12, v5
	s_movk_i32 s2, 0x500
	s_cmpk_lt_u32 s12, 0xa80
	v_cmp_gt_i32_e32 vcc, s2, v0
	s_cselect_b64 s[4:5], -1, 0
	s_add_i32 s2, s12, 0xfffff540
	s_cmpk_lt_u32 s2, 0x1000
	v_add_u32_e32 v1, -16, v0
	s_cselect_b64 s[2:3], -1, 0
	v_cndmask_b32_e64 v1, -1, v1, s[2:3]
	s_movk_i32 s2, 0xab0
	v_cmp_gt_u32_e64 s[2:3], s2, v0
	v_add_u32_e32 v2, 0xfffffd00, v0
	v_add_u32_e32 v3, 0xfffffa80, v0
	v_cndmask_b32_e64 v1, v1, v0, s[2:3]
	s_movk_i32 s2, 0xaac
	v_cmp_gt_u32_e64 s[2:3], s2, v0
	v_ashrrev_i32_e32 v4, 4, v9
	v_add_u32_e32 v6, s20, v4
	v_cndmask_b32_e64 v1, v1, v2, s[2:3]
	s_movk_i32 s2, 0xaa0
	v_cmp_gt_u32_e64 s[2:3], s2, v0
	s_waitcnt vmcnt(63) expcnt(7) lgkmcnt(15)
	s_barrier
	v_cndmask_b32_e64 v1, v1, v3, s[2:3]
	s_or_b64 s[2:3], vcc, s[4:5]
	s_cmpk_lt_u32 s12, 0x780
	s_cselect_b32 s4, 32, 44
	v_mov_b32_e32 v2, s4
	v_cndmask_b32_e64 v2, v2, 0, vcc
	v_add_u32_e32 v0, v2, v0
	v_cndmask_b32_e64 v188, v1, v0, s[2:3]
	v_mov_b32_e32 v0, 0
	v_cmp_lt_i32_e64 s[2:3], -1, v188
	v_mov_b32_e32 v1, v0
	v_mov_b32_e32 v2, v0
	v_mov_b32_e32 v3, v0
	s_and_saveexec_b64 s[4:5], s[2:3]
	s_cbranch_execz .LBB0_1996
	v_mov_b64_e32 v[0:1], s[34:35]
	s_movk_i32 s16, 0x6ac0
	v_mad_i64_i32 v[0:1], s[84:85], v6, s16, v[0:1]
	v_lshl_add_u64 v[0:1], v[188:189], 2, v[0:1]
	v_add_u32_e32 v210, 16, v6
	v_mov_b64_e32 v[212:213], s[34:35]
	v_mad_i64_i32 v[212:213], s[98:99], v210, s16, v[212:213]
	v_lshl_add_u64 v[212:213], v[188:189], 2, v[212:213]
	global_load_dwordx4 v[240:243], v[212:213], off
	v_add_u32_e32 v210, 32, v6
	v_mov_b64_e32 v[212:213], s[34:35]
	v_mad_i64_i32 v[212:213], s[98:99], v210, s16, v[212:213]
	v_lshl_add_u64 v[212:213], v[188:189], 2, v[212:213]
	global_load_dwordx4 v[244:247], v[212:213], off
	v_add_u32_e32 v210, 48, v6
	v_mov_b64_e32 v[212:213], s[34:35]
	v_mad_i64_i32 v[212:213], s[98:99], v210, s16, v[212:213]
	v_lshl_add_u64 v[212:213], v[188:189], 2, v[212:213]
	global_load_dwordx4 v[248:251], v[212:213], off
	global_load_dwordx4 v[0:3], v[0:1], off
